# GEMM K-loop heads aligned to 64 bytes (code placement pinned)
# baseline (speedup 1.0000x reference)
; #define G_STAGE(bufoff, gbase, rows, ldbv) do { _Pragma("unroll") for (int _i = 0; _i < 2; ++_i) \
;         __builtin_amdgcn_global_load_lds((const unsigned*)((const char*)(gbase) + (unsigned)((rows)[_i] * (ldbv) + c2[_i])), (LAS unsigned*)(lds + (bufoff) + ldsw + _i * 8192), 16, 0, 0); } while (0)
; #define G_LDA(dst, b, h) do { _Pragma("unroll") for (int m = 0; m < 4; ++m) _Pragma("unroll") for (int k = 0; k < 2; ++k) dst[m][k] = *(const LAS bf16x8*)(lds + G_SA(b, h) + aoff + m * 2048 + k * 1024); } while (0)
; #define G_LDB(dst, b, h) do { _Pragma("unroll") for (int n = 0; n < 2; ++n) _Pragma("unroll") for (int k = 0; k < 2; ++k) dst[n][k] = *(const LAS bf16x8*)(lds + G_SB(b, h) + boff + n * 2048 + k * 1024); } while (0)
; #define G_SCHED __builtin_amdgcn_sched_barrier(0)
; template <int PH>
; DI void gemm_phase(const Params& p, LAS unsigned char* lds, int mode) {
;     ...
;     for (;;) {
;         const bool has_next = get_unit<PH>(p, ui + 1, nxt, mode);
;         const char* nA = has_next ? nxt.A : cA; const char* nB = has_next ? nxt.B : cB; const int nl = has_next ? nxt.ldb : cl; const size_t nh = (size_t)128 * nl;
;         const int nt = cur.nt;
;         for (int t = 0; t < nt; t += 2) {
;             const bool last = (t == nt - 2);
;             const char* a1 = cA + (size_t)(t + 1) * 128;
;             const char* a2 = last ? nA : cA + (size_t)(t + 2) * 128; const char* b2 = last ? nB : cB + (size_t)(t + 2) * 128;
;             const int l2 = last ? nl : cl; const size_t h2 = last ? nh : ch;
;             const char* a3 = a2 + 128; const char* b3 = b2 + 128;
;             if (GEMM_SP2) {
;                 G_LDB(B0, 0, 0); G_LDB(B1, 0, 1); G_SCHED; G_LDA(At, 0, 0); G_STAGE(G_SA(1, 1), a1 + ch, rA, cl);
.LBB0_196:
	s_add_u32 s88, s4, 0x100
	s_addc_u32 s89, s5, 0
	v_lshl_add_u64 v[128:129], s[14:15], 0, v[176:177]
	v_lshl_add_u64 v[130:131], s[14:15], 0, v[178:179]
	s_mov_b32 s17, -2
	s_mov_b64 s[4:5], 0
	.p2align 6

; #define G_BAR __builtin_amdgcn_s_barrier()
; template <int PH>
; DI void gemm_phase(const Params& p, LAS unsigned char* lds, int mode) {
;     ...
;         const bool has_next = get_unit<PH>(p, ui + 1, nxt, mode);
;         const char* nA = has_next ? nxt.A : cA; const char* nB = has_next ? nxt.B : cB; const int nl = has_next ? nxt.ldb : cl; const size_t nh = (size_t)128 * nl;
;         const int nt = cur.nt;
;         for (int t = 0; t < nt; t += 2) {
;             const bool last = (t == nt - 2);
;             const char* a1 = cA + (size_t)(t + 1) * 128;
;             const char* a2 = last ? nA : cA + (size_t)(t + 2) * 128; const char* b2 = last ? nB : cB + (size_t)(t + 2) * 128;
;             const int l2 = last ? nl : cl; const size_t h2 = last ? nh : ch;
;             const char* a3 = a2 + 128; const char* b3 = b2 + 128;
;     ...
; #pragma unroll
;         for (int a = 0; a < 2; ++a)
; #pragma unroll
;             for (int b = 0; b < 2; ++b)
; #pragma unroll
;                 for (int m = 0; m < 4; ++m)
; #pragma unroll
;                     for (int n = 0; n < 2; ++n) acc[a][b][m][n] = (f32x4){0.f, 0.f, 0.f, 0.f};
;         cur = nxt; cA = nA; cB = nB; cl = nl; ch = nh; ++ui;
;         if (GEMM_ALIGN) { if (wr == 1) G_BAR; }
.LBB0_1226:
	s_lshl_b32 s12, s52, 7
	s_add_i32 s39, s7, -2
	s_add_u32 s40, s40, 0x80
	s_addc_u32 s41, s41, 0
	s_add_u32 s76, s42, 0x100
	s_addc_u32 s77, s43, 0
	v_mad_u64_u32 v[0:1], s[42:43], s11, v193, v[202:203]
	v_mov_b32_e32 v1, v197
	v_lshl_add_u64 v[128:129], s[36:37], 0, v[0:1]
	v_mad_u64_u32 v[0:1], s[42:43], s11, v205, v[204:205]
	v_mov_b32_e32 v1, v197
	v_lshl_add_u64 v[130:131], s[36:37], 0, v[0:1]
	v_mov_b32_e32 v0, 0
	s_mov_b32 s42, 0
	v_mov_b32_e32 v1, v0
	v_mov_b32_e32 v2, v0
	v_mov_b32_e32 v3, v0
	v_mov_b32_e32 v4, v0
	v_mov_b32_e32 v5, v0
	v_mov_b32_e32 v6, v0
	v_mov_b32_e32 v7, v0
	v_mov_b32_e32 v16, v0
	v_mov_b32_e32 v17, v0
	v_mov_b32_e32 v18, v0
	v_mov_b32_e32 v19, v0
	v_mov_b32_e32 v20, v0
	v_mov_b32_e32 v21, v0
	v_mov_b32_e32 v22, v0
	v_mov_b32_e32 v23, v0
	v_mov_b32_e32 v32, v0
	v_mov_b32_e32 v33, v0
	v_mov_b32_e32 v34, v0
	v_mov_b32_e32 v35, v0
	v_mov_b32_e32 v36, v0
	v_mov_b32_e32 v37, v0
	v_mov_b32_e32 v38, v0
	v_mov_b32_e32 v39, v0
	v_mov_b32_e32 v48, v0
	v_mov_b32_e32 v49, v0
	v_mov_b32_e32 v50, v0
	v_mov_b32_e32 v51, v0
	v_mov_b32_e32 v52, v0
	v_mov_b32_e32 v53, v0
	v_mov_b32_e32 v54, v0
	v_mov_b32_e32 v55, v0
	v_mov_b32_e32 v8, v0
	v_mov_b32_e32 v9, v0
	v_mov_b32_e32 v10, v0
	v_mov_b32_e32 v11, v0
	v_mov_b32_e32 v12, v0
	v_mov_b32_e32 v13, v0
	v_mov_b32_e32 v14, v0
	v_mov_b32_e32 v15, v0
	v_mov_b32_e32 v24, v0
	v_mov_b32_e32 v25, v0
	v_mov_b32_e32 v26, v0
	v_mov_b32_e32 v27, v0
	v_mov_b32_e32 v28, v0
	v_mov_b32_e32 v29, v0
	v_mov_b32_e32 v30, v0
	v_mov_b32_e32 v31, v0
	v_mov_b32_e32 v40, v0
	v_mov_b32_e32 v41, v0
	v_mov_b32_e32 v42, v0
	v_mov_b32_e32 v43, v0
	v_mov_b32_e32 v44, v0
	v_mov_b32_e32 v45, v0
	v_mov_b32_e32 v46, v0
	v_mov_b32_e32 v47, v0
	v_mov_b32_e32 v56, v0
	v_mov_b32_e32 v57, v0
	v_mov_b32_e32 v58, v0
	v_mov_b32_e32 v59, v0
	v_mov_b32_e32 v60, v0
	v_mov_b32_e32 v61, v0
	v_mov_b32_e32 v62, v0
	v_mov_b32_e32 v63, v0
	v_mov_b32_e32 v64, v0
	v_mov_b32_e32 v65, v0
	v_mov_b32_e32 v66, v0
	v_mov_b32_e32 v67, v0
	v_mov_b32_e32 v68, v0
	v_mov_b32_e32 v69, v0
	v_mov_b32_e32 v70, v0
	v_mov_b32_e32 v71, v0
	v_mov_b32_e32 v80, v0
	v_mov_b32_e32 v81, v0
	v_mov_b32_e32 v82, v0
	v_mov_b32_e32 v83, v0
	s_waitcnt vmcnt(0)
	v_mov_b32_e32 v84, v0
	v_mov_b32_e32 v85, v0
	v_mov_b32_e32 v86, v0
	v_mov_b32_e32 v87, v0
	v_mov_b32_e32 v96, v0
	v_mov_b32_e32 v97, v0
	v_mov_b32_e32 v98, v0
	v_mov_b32_e32 v99, v0
	v_mov_b32_e32 v100, v0
	v_mov_b32_e32 v101, v0
	v_mov_b32_e32 v102, v0
	v_mov_b32_e32 v103, v0
	v_mov_b32_e32 v112, v0
	v_mov_b32_e32 v113, v0
	v_mov_b32_e32 v114, v0
	v_mov_b32_e32 v115, v0
	v_mov_b32_e32 v116, v0
	v_mov_b32_e32 v117, v0
	v_mov_b32_e32 v118, v0
	v_mov_b32_e32 v119, v0
	v_mov_b32_e32 v72, v0
	v_mov_b32_e32 v73, v0
	v_mov_b32_e32 v74, v0
	v_mov_b32_e32 v75, v0
	v_mov_b32_e32 v76, v0
	v_mov_b32_e32 v77, v0
	v_mov_b32_e32 v78, v0
	v_mov_b32_e32 v79, v0
	v_mov_b32_e32 v88, v0
	v_mov_b32_e32 v89, v0
	v_mov_b32_e32 v90, v0
	v_mov_b32_e32 v91, v0
	v_mov_b32_e32 v92, v0
	v_mov_b32_e32 v93, v0
	v_mov_b32_e32 v94, v0
	v_mov_b32_e32 v95, v0
	v_mov_b32_e32 v104, v0
	v_mov_b32_e32 v105, v0
	v_mov_b32_e32 v106, v0
	v_mov_b32_e32 v107, v0
	v_mov_b32_e32 v108, v0
	v_mov_b32_e32 v109, v0
	v_mov_b32_e32 v110, v0
	v_mov_b32_e32 v111, v0
	v_mov_b32_e32 v120, v0
	v_mov_b32_e32 v121, v0
	v_mov_b32_e32 v122, v0
	v_mov_b32_e32 v123, v0
	v_mov_b32_e32 v124, v0
	v_mov_b32_e32 v125, v0
	v_mov_b32_e32 v126, v0
	v_mov_b32_e32 v127, v0
	.p2align 6

; #define G_STAGE(bufoff, gbase, rows, ldbv) do { _Pragma("unroll") for (int _i = 0; _i < 2; ++_i) \
;         __builtin_amdgcn_global_load_lds((const unsigned*)((const char*)(gbase) + (unsigned)((rows)[_i] * (ldbv) + c2[_i])), (LAS unsigned*)(lds + (bufoff) + ldsw + _i * 8192), 16, 0, 0); } while (0)
; #define G_WAIT_V(n) asm volatile("s_waitcnt vmcnt(" #n ")" ::: "memory")
; #define G_BAR __builtin_amdgcn_s_barrier()
; template <int PH>
; DI void gemm_phase(const Params& p, LAS unsigned char* lds, int mode) {
;     ...
;     Unit cur, nxt; int ui = 0;
;     if (!get_unit<PH>(p, 0, cur, mode)) return;
;     f32x4 acc[2][2][4][2];
; #pragma unroll
;     for (int a = 0; a < 2; ++a)
; #pragma unroll
;         for (int b = 0; b < 2; ++b)
; #pragma unroll
;             for (int m = 0; m < 4; ++m)
; #pragma unroll
;                 for (int n = 0; n < 2; ++n) acc[a][b][m][n] = (f32x4){0.f, 0.f, 0.f, 0.f};
;     bf16x8 At[4][2], B0[2][2], B1[2][2];
;     const char* cA = cur.A; const char* cB = cur.B; int cl = cur.ldb; size_t ch = (size_t)128 * cl;
;     if (GEMM_SP2) {
;         G_STAGE(G_SB(0, 0), cB, rB, cl); G_STAGE(G_SB(0, 1), cB + ch, rB, cl); G_STAGE(G_SA(0, 0), cA, rA, cl); G_STAGE(G_SA(0, 1), cA + ch, rA, cl);
;         if (wr == 1) G_BAR;
;         G_WAIT_V(2); G_BAR;
;         G_STAGE(G_SB(1, 0), cB + 128, rB, cl); G_STAGE(G_SA(1, 0), cA + 128, rA, cl); G_STAGE(G_SB(1, 1), cB + ch + 128, rB, cl);
;         G_WAIT_V(6); G_BAR;
;     } else {
;         G_STAGE(G_SB(0, 0), cB, rB, cl); G_STAGE(G_SA(0, 0), cA, rA, cl); G_STAGE(G_SB(0, 1), cB + ch, rB, cl); G_STAGE(G_SA(0, 1), cA + ch, rA, cl);
;         if (wr == 1) G_BAR;
;         G_WAIT_V(4); G_BAR;
;         G_STAGE(G_SB(1, 0), cB + 128, rB, cl); G_STAGE(G_SA(1, 0), cA + 128, rA, cl); G_STAGE(G_SB(1, 1), cB + ch + 128, rB, cl);
;         G_WAIT_V(6); G_BAR;
;     }
;     for (;;) {
;         const bool has_next = get_unit<PH>(p, ui + 1, nxt, mode);
;         const char* nA = has_next ? nxt.A : cA; const char* nB = has_next ? nxt.B : cB; const int nl = has_next ? nxt.ldb : cl; const size_t nh = (size_t)128 * nl;
;         const int nt = cur.nt;
;         for (int t = 0; t < nt; t += 2) {
.LBB0_1375:
	s_add_u32 s26, s26, 0x40080
	s_addc_u32 s27, s27, 0
	s_add_u32 s1, s28, 0x100
	v_mov_b32_e32 v0, 0
	s_addc_u32 s23, s29, 0
	s_mov_b32 s25, -2
	v_mov_b32_e32 v1, v0
	v_mov_b32_e32 v2, v0
	v_mov_b32_e32 v3, v0
	v_mov_b32_e32 v4, v0
	v_mov_b32_e32 v5, v0
	v_mov_b32_e32 v6, v0
	v_mov_b32_e32 v7, v0
	v_mov_b32_e32 v16, v0
	v_mov_b32_e32 v17, v0
	v_mov_b32_e32 v18, v0
	v_mov_b32_e32 v19, v0
	v_mov_b32_e32 v20, v0
	v_mov_b32_e32 v21, v0
	v_mov_b32_e32 v22, v0
	v_mov_b32_e32 v23, v0
	v_mov_b32_e32 v28, v0
	v_mov_b32_e32 v29, v0
	v_mov_b32_e32 v30, v0
	v_mov_b32_e32 v31, v0
	v_mov_b32_e32 v36, v0
	v_mov_b32_e32 v37, v0
	v_mov_b32_e32 v38, v0
	v_mov_b32_e32 v39, v0
	v_mov_b32_e32 v44, v0
	v_mov_b32_e32 v45, v0
	v_mov_b32_e32 v46, v0
	v_mov_b32_e32 v47, v0
	v_mov_b32_e32 v52, v0
	v_mov_b32_e32 v53, v0
	v_mov_b32_e32 v54, v0
	v_mov_b32_e32 v55, v0
	v_mov_b32_e32 v8, v0
	v_mov_b32_e32 v9, v0
	v_mov_b32_e32 v10, v0
	v_mov_b32_e32 v11, v0
	v_mov_b32_e32 v12, v0
	v_mov_b32_e32 v13, v0
	v_mov_b32_e32 v14, v0
	v_mov_b32_e32 v15, v0
	v_mov_b32_e32 v24, v0
	v_mov_b32_e32 v25, v0
	v_mov_b32_e32 v26, v0
	v_mov_b32_e32 v27, v0
	v_mov_b32_e32 v32, v0
	v_mov_b32_e32 v33, v0
	v_mov_b32_e32 v34, v0
	v_mov_b32_e32 v35, v0
	v_mov_b32_e32 v40, v0
	v_mov_b32_e32 v41, v0
	v_mov_b32_e32 v42, v0
	v_mov_b32_e32 v43, v0
	v_mov_b32_e32 v48, v0
	v_mov_b32_e32 v49, v0
	v_mov_b32_e32 v50, v0
	v_mov_b32_e32 v51, v0
	v_mov_b32_e32 v56, v0
	v_mov_b32_e32 v57, v0
	v_mov_b32_e32 v58, v0
	v_mov_b32_e32 v59, v0
	v_mov_b32_e32 v60, v0
	v_mov_b32_e32 v61, v0
	v_mov_b32_e32 v62, v0
	v_mov_b32_e32 v63, v0
	v_mov_b32_e32 v64, v0
	v_mov_b32_e32 v65, v0
	v_mov_b32_e32 v66, v0
	v_mov_b32_e32 v67, v0
	v_mov_b32_e32 v68, v0
	v_mov_b32_e32 v69, v0
	v_mov_b32_e32 v70, v0
	v_mov_b32_e32 v71, v0
	v_mov_b32_e32 v80, v0
	v_mov_b32_e32 v81, v0
	v_mov_b32_e32 v82, v0
	v_mov_b32_e32 v83, v0
	v_mov_b32_e32 v84, v0
	v_mov_b32_e32 v85, v0
	v_mov_b32_e32 v86, v0
	v_mov_b32_e32 v87, v0
	v_mov_b32_e32 v92, v0
	v_mov_b32_e32 v93, v0
	v_mov_b32_e32 v94, v0
	v_mov_b32_e32 v95, v0
	v_mov_b32_e32 v100, v0
	v_mov_b32_e32 v101, v0
	v_mov_b32_e32 v102, v0
	v_mov_b32_e32 v103, v0
	v_mov_b32_e32 v108, v0
	v_mov_b32_e32 v109, v0
	v_mov_b32_e32 v110, v0
	v_mov_b32_e32 v111, v0
	v_mov_b32_e32 v116, v0
	v_mov_b32_e32 v117, v0
	v_mov_b32_e32 v118, v0
	v_mov_b32_e32 v119, v0
	v_mov_b32_e32 v72, v0
	v_mov_b32_e32 v73, v0
	v_mov_b32_e32 v74, v0
	v_mov_b32_e32 v75, v0
	v_mov_b32_e32 v76, v0
	v_mov_b32_e32 v77, v0
	v_mov_b32_e32 v78, v0
	v_mov_b32_e32 v79, v0
	v_mov_b32_e32 v88, v0
	v_mov_b32_e32 v89, v0
	v_mov_b32_e32 v90, v0
	v_mov_b32_e32 v91, v0
	v_mov_b32_e32 v96, v0
	v_mov_b32_e32 v97, v0
	v_mov_b32_e32 v98, v0
	v_mov_b32_e32 v99, v0
	v_mov_b32_e32 v104, v0
	v_mov_b32_e32 v105, v0
	v_mov_b32_e32 v106, v0
	v_mov_b32_e32 v107, v0
	v_mov_b32_e32 v112, v0
	v_mov_b32_e32 v113, v0
	v_mov_b32_e32 v114, v0
	v_mov_b32_e32 v115, v0
	v_mov_b32_e32 v120, v0
	v_mov_b32_e32 v121, v0
	v_mov_b32_e32 v122, v0
	v_mov_b32_e32 v123, v0
	v_mov_b32_e32 v124, v0
	v_mov_b32_e32 v125, v0
	v_mov_b32_e32 v126, v0
	v_mov_b32_e32 v127, v0
	.p2align 6
